# nt cache policy on all read-once streams (prep f32 weights and x, rms ORAW/G, sample state, final) + barrier poll sleep 4
# speedup vs baseline: 1.0115x; 1.0048x over previous
.LBB0_50:
	s_ashr_i32 s13, s12, 31
	s_lshl_b64 s[28:29], s[12:13], 2
	s_add_u32 s10, s34, s28
	s_addc_u32 s11, s35, s29
	v_lshl_add_u64 v[20:21], s[10:11], 0, v[76:77]
	v_mul_lo_u32 v2, s37, v74
	v_mul_lo_u32 v3, s36, v75
	v_mad_u64_u32 v[0:1], s[10:11], s36, v74, 0
	v_add3_u32 v1, v1, v3, v2
	v_lshl_add_u64 v[0:1], v[0:1], 2, v[20:21]
	global_load_dwordx4 v[0:3], v[0:1], off nt
	s_cmp_lg_u64 s[20:21], 0
	s_cselect_b64 s[12:13], -1, 0
	s_cmp_eq_u64 s[20:21], 0
	v_lshl_add_u64 v[36:37], v[74:75], 2, s[20:21]
	s_cbranch_scc1 .LBB0_52
	global_load_dword v116, v[36:37], off
	s_branch .LBB0_53

.LBB0_56:
	v_mul_lo_u32 v6, s37, v78
	v_mul_lo_u32 v7, s36, v73
	v_mad_u64_u32 v[4:5], s[10:11], s36, v78, 0
	v_add3_u32 v5, v5, v7, v6
	v_lshl_add_u64 v[4:5], v[4:5], 2, v[20:21]
	global_load_dwordx4 v[4:7], v[4:5], off nt
	v_cndmask_b32_e64 v8, 0, 1, s[12:13]
	v_cmp_ne_u32_e64 s[10:11], 1, v8
	s_andn2_b64 vcc, exec, s[12:13]
	s_cbranch_vccnz .LBB0_59
	global_load_dword v118, v[36:37], off offset:128
	v_cndmask_b32_e64 v8, 0, 1, s[38:39]
	v_cmp_ne_u32_e64 s[12:13], 1, v8
	s_andn2_b64 vcc, exec, s[38:39]
	s_cbranch_vccnz .LBB0_60

.LBB0_61:
	v_mul_lo_u32 v10, s37, v80
	v_mul_lo_u32 v11, s36, v79
	v_mad_u64_u32 v[8:9], s[38:39], s36, v80, 0
	v_add3_u32 v9, v9, v11, v10
	v_lshl_add_u64 v[8:9], v[8:9], 2, v[20:21]
	global_load_dwordx4 v[8:11], v[8:9], off nt
	s_and_b64 vcc, exec, s[10:11]
	s_cbranch_vccnz .LBB0_64
	global_load_dword v122, v[36:37], off offset:256
	s_and_b64 vcc, exec, s[12:13]
	s_cbranch_vccnz .LBB0_65

.LBB0_66:
	v_mul_lo_u32 v14, s37, v82
	v_mul_lo_u32 v15, s36, v81
	v_mad_u64_u32 v[12:13], s[38:39], s36, v82, 0
	v_add3_u32 v13, v13, v15, v14
	v_lshl_add_u64 v[12:13], v[12:13], 2, v[20:21]
	global_load_dwordx4 v[12:15], v[12:13], off nt
	s_and_b64 vcc, exec, s[10:11]
	s_cbranch_vccnz .LBB0_69
	global_load_dword v128, v[36:37], off offset:384
	s_and_b64 vcc, exec, s[12:13]
	s_cbranch_vccnz .LBB0_70

.LBB0_71:
	v_mul_lo_u32 v18, s37, v84
	v_mul_lo_u32 v19, s36, v83
	v_mad_u64_u32 v[16:17], s[38:39], s36, v84, 0
	v_add3_u32 v17, v17, v19, v18
	v_lshl_add_u64 v[16:17], v[16:17], 2, v[20:21]
	global_load_dwordx4 v[16:19], v[16:17], off nt
	s_and_b64 vcc, exec, s[10:11]
	s_cbranch_vccnz .LBB0_74
	global_load_dword v134, v[36:37], off offset:512
	s_and_b64 vcc, exec, s[12:13]
	s_cbranch_vccnz .LBB0_75

.LBB0_76:
	v_mul_lo_u32 v26, s37, v86
	v_mul_lo_u32 v27, s36, v85
	v_mad_u64_u32 v[24:25], s[38:39], s36, v86, 0
	v_add3_u32 v25, v25, v27, v26
	v_lshl_add_u64 v[24:25], v[24:25], 2, v[20:21]
	global_load_dwordx4 v[24:27], v[24:25], off nt
	s_and_b64 vcc, exec, s[10:11]
	s_cbranch_vccnz .LBB0_79
	global_load_dword v144, v[36:37], off offset:640
	s_and_b64 vcc, exec, s[12:13]
	s_cbranch_vccnz .LBB0_80

.LBB0_81:
	v_mul_lo_u32 v30, s37, v88
	v_mul_lo_u32 v31, s36, v87
	v_mad_u64_u32 v[28:29], s[38:39], s36, v88, 0
	v_add3_u32 v29, v29, v31, v30
	v_lshl_add_u64 v[28:29], v[28:29], 2, v[20:21]
	global_load_dwordx4 v[28:31], v[28:29], off nt
	s_and_b64 vcc, exec, s[10:11]
	s_cbranch_vccnz .LBB0_84
	global_load_dword v158, v[36:37], off offset:768
	s_and_b64 vcc, exec, s[12:13]
	s_cbranch_vccnz .LBB0_85

.LBB0_86:
	v_mul_lo_u32 v34, s37, v90
	v_mul_lo_u32 v35, s36, v89
	v_mad_u64_u32 v[32:33], s[38:39], s36, v90, 0
	v_add3_u32 v33, v33, v35, v34
	v_lshl_add_u64 v[20:21], v[32:33], 2, v[20:21]
	global_load_dwordx4 v[32:35], v[20:21], off nt
	s_and_b64 vcc, exec, s[10:11]
	s_cbranch_vccnz .LBB0_128
	global_load_dword v164, v[36:37], off offset:896
	v_mov_b32_e32 v20, 0
	s_and_b64 vcc, exec, s[12:13]
	v_mov_b32_e32 v140, 0
	s_cbranch_vccnz .LBB0_89

.LBB0_93:
	s_waitcnt vmcnt(7)
	v_pk_mul_f32 v[40:41], v[0:1], v[116:117] op_sel_hi:[1,0]
	v_pk_mul_f32 v[42:43], v[2:3], v[116:117] op_sel_hi:[1,0]
	v_and_b32_sdwa v70, v41, v127 dst_sel:DWORD dst_unused:UNUSED_PAD src0_sel:WORD_1 src1_sel:DWORD
	v_and_b32_sdwa v71, v40, v127 dst_sel:DWORD dst_unused:UNUSED_PAD src0_sel:WORD_1 src1_sel:DWORD
	s_waitcnt vmcnt(6)
	v_pk_mul_f32 v[44:45], v[4:5], v[118:119] op_sel_hi:[1,0]
	v_and_b32_sdwa v129, v43, v127 dst_sel:DWORD dst_unused:UNUSED_PAD src0_sel:WORD_1 src1_sel:DWORD
	s_waitcnt vmcnt(5)
	v_pk_mul_f32 v[48:49], v[8:9], v[122:123] op_sel_hi:[1,0]
	v_add3_u32 v171, v41, v70, s66
	v_add3_u32 v172, v40, v71, s66
	v_and_b32_sdwa v40, v45, v127 dst_sel:DWORD dst_unused:UNUSED_PAD src0_sel:WORD_1 src1_sel:DWORD
	v_and_b32_sdwa v41, v44, v127 dst_sel:DWORD dst_unused:UNUSED_PAD src0_sel:WORD_1 src1_sel:DWORD
	v_and_b32_sdwa v131, v42, v127 dst_sel:DWORD dst_unused:UNUSED_PAD src0_sel:WORD_1 src1_sel:DWORD
	v_pk_mul_f32 v[46:47], v[6:7], v[118:119] op_sel_hi:[1,0]
	s_waitcnt vmcnt(4)
	v_pk_mul_f32 v[52:53], v[12:13], v[128:129] op_sel_hi:[1,0]
	v_add3_u32 v175, v45, v40, s66
	v_add3_u32 v176, v44, v41, s66
	v_and_b32_sdwa v40, v49, v127 dst_sel:DWORD dst_unused:UNUSED_PAD src0_sel:WORD_1 src1_sel:DWORD
	v_and_b32_sdwa v41, v48, v127 dst_sel:DWORD dst_unused:UNUSED_PAD src0_sel:WORD_1 src1_sel:DWORD
	v_pk_mul_f32 v[50:51], v[10:11], v[122:123] op_sel_hi:[1,0]
	s_waitcnt vmcnt(3)
	v_pk_mul_f32 v[56:57], v[16:17], v[134:135] op_sel_hi:[1,0]
	v_pk_mul_f32 v[58:59], v[18:19], v[134:135] op_sel_hi:[1,0]
	v_add3_u32 v179, v49, v40, s66
	v_add3_u32 v180, v48, v41, s66
	v_and_b32_sdwa v40, v53, v127 dst_sel:DWORD dst_unused:UNUSED_PAD src0_sel:WORD_1 src1_sel:DWORD
	v_and_b32_sdwa v41, v52, v127 dst_sel:DWORD dst_unused:UNUSED_PAD src0_sel:WORD_1 src1_sel:DWORD
	v_add3_u32 v133, v43, v129, s66
	v_add3_u32 v135, v42, v131, s66
	v_and_b32_sdwa v42, v47, v127 dst_sel:DWORD dst_unused:UNUSED_PAD src0_sel:WORD_1 src1_sel:DWORD
	v_and_b32_sdwa v43, v46, v127 dst_sel:DWORD dst_unused:UNUSED_PAD src0_sel:WORD_1 src1_sel:DWORD
	v_pk_mul_f32 v[54:55], v[14:15], v[128:129] op_sel_hi:[1,0]
	s_waitcnt vmcnt(2)
	v_pk_mul_f32 v[60:61], v[24:25], v[144:145] op_sel_hi:[1,0]
	v_add3_u32 v183, v53, v40, s66
	v_add3_u32 v184, v52, v41, s66
	v_and_b32_sdwa v40, v57, v127 dst_sel:DWORD dst_unused:UNUSED_PAD src0_sel:WORD_1 src1_sel:DWORD
	v_and_b32_sdwa v41, v56, v127 dst_sel:DWORD dst_unused:UNUSED_PAD src0_sel:WORD_1 src1_sel:DWORD
	v_add3_u32 v137, v47, v42, s66
	v_add3_u32 v139, v46, v43, s66
	v_and_b32_sdwa v42, v51, v127 dst_sel:DWORD dst_unused:UNUSED_PAD src0_sel:WORD_1 src1_sel:DWORD
	v_and_b32_sdwa v43, v50, v127 dst_sel:DWORD dst_unused:UNUSED_PAD src0_sel:WORD_1 src1_sel:DWORD
	v_pk_mul_f32 v[62:63], v[26:27], v[144:145] op_sel_hi:[1,0]
	s_waitcnt vmcnt(1)
	v_pk_mul_f32 v[64:65], v[28:29], v[158:159] op_sel_hi:[1,0]
	v_add3_u32 v185, v57, v40, s66
	v_add3_u32 v186, v56, v41, s66
	v_and_b32_sdwa v40, v61, v127 dst_sel:DWORD dst_unused:UNUSED_PAD src0_sel:WORD_1 src1_sel:DWORD
	v_and_b32_sdwa v41, v60, v127 dst_sel:DWORD dst_unused:UNUSED_PAD src0_sel:WORD_1 src1_sel:DWORD
	v_add3_u32 v141, v51, v42, s66
	v_add3_u32 v145, v50, v43, s66
	v_and_b32_sdwa v42, v55, v127 dst_sel:DWORD dst_unused:UNUSED_PAD src0_sel:WORD_1 src1_sel:DWORD
	v_and_b32_sdwa v43, v54, v127 dst_sel:DWORD dst_unused:UNUSED_PAD src0_sel:WORD_1 src1_sel:DWORD
	v_pk_mul_f32 v[66:67], v[30:31], v[158:159] op_sel_hi:[1,0]
	s_waitcnt vmcnt(0)
	v_pk_mul_f32 v[68:69], v[32:33], v[164:165] op_sel_hi:[1,0]
	v_add3_u32 v187, v61, v40, s66
	v_add3_u32 v188, v60, v41, s66
	v_and_b32_sdwa v40, v65, v127 dst_sel:DWORD dst_unused:UNUSED_PAD src0_sel:WORD_1 src1_sel:DWORD
	v_and_b32_sdwa v41, v64, v127 dst_sel:DWORD dst_unused:UNUSED_PAD src0_sel:WORD_1 src1_sel:DWORD
	v_add3_u32 v159, v55, v42, s66
	v_add3_u32 v168, v54, v43, s66
	v_and_b32_sdwa v42, v59, v127 dst_sel:DWORD dst_unused:UNUSED_PAD src0_sel:WORD_1 src1_sel:DWORD
	v_and_b32_sdwa v43, v58, v127 dst_sel:DWORD dst_unused:UNUSED_PAD src0_sel:WORD_1 src1_sel:DWORD
	v_add3_u32 v189, v65, v40, s66
	v_add3_u32 v190, v64, v41, s66
	v_and_b32_sdwa v40, v69, v127 dst_sel:DWORD dst_unused:UNUSED_PAD src0_sel:WORD_1 src1_sel:DWORD
	v_and_b32_sdwa v41, v68, v127 dst_sel:DWORD dst_unused:UNUSED_PAD src0_sel:WORD_1 src1_sel:DWORD
	v_add3_u32 v169, v59, v42, s66
	v_add3_u32 v170, v58, v43, s66
	v_and_b32_sdwa v42, v63, v127 dst_sel:DWORD dst_unused:UNUSED_PAD src0_sel:WORD_1 src1_sel:DWORD
	v_and_b32_sdwa v43, v62, v127 dst_sel:DWORD dst_unused:UNUSED_PAD src0_sel:WORD_1 src1_sel:DWORD
	v_add3_u32 v191, v69, v40, s66
	v_add3_u32 v192, v68, v41, s66
	v_pk_mul_f32 v[40:41], v[34:35], v[164:165] op_sel_hi:[1,0]
	v_add3_u32 v173, v63, v42, s66
	v_add3_u32 v174, v62, v43, s66
	v_and_b32_sdwa v42, v67, v127 dst_sel:DWORD dst_unused:UNUSED_PAD src0_sel:WORD_1 src1_sel:DWORD
	v_and_b32_sdwa v43, v66, v127 dst_sel:DWORD dst_unused:UNUSED_PAD src0_sel:WORD_1 src1_sel:DWORD
	s_addk_i32 s36, 0x100
	v_add3_u32 v177, v67, v42, s66
	v_add3_u32 v178, v66, v43, s66
	v_and_b32_sdwa v42, v41, v127 dst_sel:DWORD dst_unused:UNUSED_PAD src0_sel:WORD_1 src1_sel:DWORD
	v_and_b32_sdwa v43, v40, v127 dst_sel:DWORD dst_unused:UNUSED_PAD src0_sel:WORD_1 src1_sel:DWORD
	s_cmp_ge_u32 s36, s68
	v_add3_u32 v181, v41, v42, s66
	v_add3_u32 v182, v40, v43, s66
	s_cselect_b64 s[34:35], -1, 0
	s_cmp_lt_u32 s36, s68
	v_mov_b64_e32 v[58:59], v[18:19]
	v_mov_b64_e32 v[56:57], v[16:17]
	v_mov_b64_e32 v[42:43], v[2:3]
	v_mov_b64_e32 v[46:47], v[6:7]
	v_mov_b64_e32 v[50:51], v[10:11]
	v_mov_b64_e32 v[54:55], v[14:15]
	v_mov_b64_e32 v[40:41], v[0:1]
	v_mov_b64_e32 v[44:45], v[4:5]
	v_mov_b64_e32 v[48:49], v[8:9]
	v_mov_b64_e32 v[52:53], v[12:13]
	v_mov_b64_e32 v[70:71], v[34:35]
	v_mov_b64_e32 v[68:69], v[32:33]
	v_mov_b64_e32 v[66:67], v[30:31]
	v_mov_b64_e32 v[64:65], v[28:29]
	v_mov_b64_e32 v[62:63], v[26:27]
	v_mov_b64_e32 v[60:61], v[24:25]
	v_mov_b32_e32 v129, v120
	v_mov_b32_e32 v131, v124
	v_mov_b32_e32 v193, v126
	v_mov_b32_e32 v194, v130
	v_mov_b32_e32 v195, v132
	v_mov_b32_e32 v196, v136
	v_mov_b32_e32 v197, v138
	v_mov_b32_e32 v165, v140
	ds_write_b16_d16_hi v123, v172
	ds_write_b16_d16_hi v123, v171 offset:528
	ds_write_b16_d16_hi v123, v176 offset:64
	ds_write_b16_d16_hi v123, v175 offset:592
	ds_write_b16_d16_hi v123, v180 offset:128
	ds_write_b16_d16_hi v123, v179 offset:656
	ds_write_b16_d16_hi v123, v184 offset:192
	ds_write_b16_d16_hi v123, v183 offset:720
	ds_write_b16_d16_hi v123, v186 offset:256
	ds_write_b16_d16_hi v123, v185 offset:784
	ds_write_b16_d16_hi v123, v188 offset:320
	ds_write_b16_d16_hi v123, v187 offset:848
	ds_write_b16_d16_hi v123, v190 offset:384
	ds_write_b16_d16_hi v123, v189 offset:912
	ds_write_b16_d16_hi v123, v192 offset:448
	ds_write_b16_d16_hi v123, v191 offset:976
	ds_write_b16_d16_hi v123, v135 offset:1056
	ds_write_b16_d16_hi v123, v133 offset:1584
	ds_write_b16_d16_hi v123, v139 offset:1120
	ds_write_b16_d16_hi v123, v137 offset:1648
	ds_write_b16_d16_hi v123, v145 offset:1184
	ds_write_b16_d16_hi v123, v141 offset:1712
	ds_write_b16_d16_hi v123, v168 offset:1248
	ds_write_b16_d16_hi v123, v159 offset:1776
	ds_write_b16_d16_hi v123, v170 offset:1312
	ds_write_b16_d16_hi v123, v169 offset:1840
	ds_write_b16_d16_hi v123, v174 offset:1376
	ds_write_b16_d16_hi v123, v173 offset:1904
	ds_write_b16_d16_hi v123, v178 offset:1440
	ds_write_b16_d16_hi v123, v177 offset:1968
	ds_write_b16_d16_hi v123, v182 offset:1504
	ds_write_b16_d16_hi v123, v181 offset:2032
	s_cbranch_scc0 .LBB0_92
	v_lshl_add_u64 v[40:41], v[148:149], 0, s[28:29]
	global_load_dwordx4 v[40:43], v[40:41], off nt
	s_and_b64 vcc, exec, s[10:11]
	v_lshl_add_u64 v[164:165], s[20:21], 0, v[92:93]
	s_cbranch_vccnz .LBB0_109
	global_load_dword v116, v[164:165], off offset:1024
	s_and_b64 vcc, exec, s[12:13]
	v_lshl_add_u64 v[166:167], s[22:23], 0, v[92:93]
	s_cbranch_vccnz .LBB0_110
.LBB0_96:
	global_load_dword v129, v[166:167], off offset:1024
	v_lshl_add_u64 v[44:45], v[152:153], 0, s[28:29]
	global_load_dwordx4 v[44:47], v[44:45], off nt
	s_and_b64 vcc, exec, s[10:11]
	s_cbranch_vccnz .LBB0_111

.LBB0_98:
	global_load_dword v131, v[166:167], off offset:1152
	v_lshl_add_u64 v[48:49], v[156:157], 0, s[28:29]
	global_load_dwordx4 v[48:51], v[48:49], off nt
	s_and_b64 vcc, exec, s[10:11]
	s_cbranch_vccnz .LBB0_113

.LBB0_100:
	global_load_dword v193, v[166:167], off offset:1280
	v_lshl_add_u64 v[52:53], v[162:163], 0, s[28:29]
	global_load_dwordx4 v[52:55], v[52:53], off offset:-8 nt
	s_and_b64 vcc, exec, s[10:11]
	s_cbranch_vccnz .LBB0_115

.LBB0_102:
	global_load_dword v194, v[166:167], off offset:1408
	v_lshl_add_u64 v[56:57], v[160:161], 0, s[28:29]
	global_load_dwordx4 v[56:59], v[56:57], off offset:-8 nt
	s_and_b64 vcc, exec, s[10:11]
	s_cbranch_vccnz .LBB0_117

.LBB0_104:
	global_load_dword v195, v[166:167], off offset:1536
	v_lshl_add_u64 v[60:61], v[154:155], 0, s[28:29]
	global_load_dwordx4 v[60:63], v[60:61], off offset:-8 nt
	s_and_b64 vcc, exec, s[10:11]
	s_cbranch_vccnz .LBB0_119

.LBB0_106:
	global_load_dword v196, v[166:167], off offset:1664
	v_lshl_add_u64 v[64:65], v[150:151], 0, s[28:29]
	global_load_dwordx4 v[64:67], v[64:65], off offset:-8 nt
	s_and_b64 vcc, exec, s[10:11]
	s_cbranch_vccnz .LBB0_121

.LBB0_108:
	global_load_dword v197, v[166:167], off offset:1792
	v_lshl_add_u64 v[68:69], v[146:147], 0, s[28:29]
	global_load_dwordx4 v[68:71], v[68:69], off offset:-8 nt
	s_and_b64 vcc, exec, s[10:11]
	s_cbranch_vccz .LBB0_123
	s_branch .LBB0_90

.LBB0_110:
	v_mov_b32_e32 v129, 0
	v_lshl_add_u64 v[44:45], v[152:153], 0, s[28:29]
	global_load_dwordx4 v[44:47], v[44:45], off nt
	s_and_b64 vcc, exec, s[10:11]
	s_cbranch_vccz .LBB0_97

.LBB0_112:
	v_mov_b32_e32 v131, 0
	v_lshl_add_u64 v[48:49], v[156:157], 0, s[28:29]
	global_load_dwordx4 v[48:51], v[48:49], off nt
	s_and_b64 vcc, exec, s[10:11]
	s_cbranch_vccz .LBB0_99

.LBB0_114:
	v_mov_b32_e32 v193, 0
	v_lshl_add_u64 v[52:53], v[162:163], 0, s[28:29]
	global_load_dwordx4 v[52:55], v[52:53], off offset:-8 nt
	s_and_b64 vcc, exec, s[10:11]
	s_cbranch_vccz .LBB0_101

.LBB0_116:
	v_mov_b32_e32 v194, 0
	v_lshl_add_u64 v[56:57], v[160:161], 0, s[28:29]
	global_load_dwordx4 v[56:59], v[56:57], off offset:-8 nt
	s_and_b64 vcc, exec, s[10:11]
	s_cbranch_vccz .LBB0_103

.LBB0_118:
	v_mov_b32_e32 v195, 0
	v_lshl_add_u64 v[60:61], v[154:155], 0, s[28:29]
	global_load_dwordx4 v[60:63], v[60:61], off offset:-8 nt
	s_and_b64 vcc, exec, s[10:11]
	s_cbranch_vccz .LBB0_105

.LBB0_120:
	v_mov_b32_e32 v196, 0
	v_lshl_add_u64 v[64:65], v[150:151], 0, s[28:29]
	global_load_dwordx4 v[64:67], v[64:65], off offset:-8 nt
	s_and_b64 vcc, exec, s[10:11]
	s_cbranch_vccz .LBB0_107

.LBB0_122:
	v_mov_b32_e32 v197, 0
	v_lshl_add_u64 v[68:69], v[146:147], 0, s[28:29]
	global_load_dwordx4 v[68:71], v[68:69], off offset:-8 nt
	s_and_b64 vcc, exec, s[10:11]
	s_cbranch_vccnz .LBB0_90

.Lx8_loop:
	v_lshl_add_u64 v[132:133], s[72:73], 0, v[2:3]
	global_load_dwordx4 v[100:103], v[132:133], off nt
	v_lshl_add_u64 v[2:3], v[2:3], 0, s[10:11]
	v_lshl_add_u64 v[0:1], v[0:1], 0, s[6:7]
	v_lshl_add_u64 v[132:133], s[72:73], 0, v[2:3]
	global_load_dwordx4 v[104:107], v[132:133], off nt
	v_lshl_add_u64 v[2:3], v[2:3], 0, s[10:11]
	v_lshl_add_u64 v[0:1], v[0:1], 0, s[6:7]
	v_lshl_add_u64 v[132:133], s[72:73], 0, v[2:3]
	global_load_dwordx4 v[108:111], v[132:133], off nt
	v_lshl_add_u64 v[2:3], v[2:3], 0, s[10:11]
	v_lshl_add_u64 v[0:1], v[0:1], 0, s[6:7]
	v_lshl_add_u64 v[132:133], s[72:73], 0, v[2:3]
	global_load_dwordx4 v[112:115], v[132:133], off nt
	v_lshl_add_u64 v[2:3], v[2:3], 0, s[10:11]
	v_lshl_add_u64 v[0:1], v[0:1], 0, s[6:7]
	v_lshl_add_u64 v[132:133], s[72:73], 0, v[2:3]
	global_load_dwordx4 v[116:119], v[132:133], off nt
	v_lshl_add_u64 v[2:3], v[2:3], 0, s[10:11]
	v_lshl_add_u64 v[0:1], v[0:1], 0, s[6:7]
	v_lshl_add_u64 v[132:133], s[72:73], 0, v[2:3]
	global_load_dwordx4 v[120:123], v[132:133], off nt
	v_lshl_add_u64 v[2:3], v[2:3], 0, s[10:11]
	v_lshl_add_u64 v[0:1], v[0:1], 0, s[6:7]
	v_lshl_add_u64 v[132:133], s[72:73], 0, v[2:3]
	global_load_dwordx4 v[124:127], v[132:133], off nt
	v_lshl_add_u64 v[2:3], v[2:3], 0, s[10:11]
	v_lshl_add_u64 v[0:1], v[0:1], 0, s[6:7]
	v_lshl_add_u64 v[132:133], s[72:73], 0, v[2:3]
	global_load_dwordx4 v[128:131], v[132:133], off nt
	v_lshl_add_u64 v[2:3], v[2:3], 0, s[10:11]
	v_lshl_add_u64 v[0:1], v[0:1], 0, s[6:7]
	s_waitcnt vmcnt(7)
	v_cvt_pk_bf16_f32 v100, v100, v101
	v_cvt_pk_bf16_f32 v101, v102, v103
	global_store_dwordx2 v[4:5], v[100:101], off
	v_lshl_add_u64 v[4:5], v[4:5], 0, s[12:13]
	s_waitcnt vmcnt(7)
	v_cvt_pk_bf16_f32 v104, v104, v105
	v_cvt_pk_bf16_f32 v105, v106, v107
	global_store_dwordx2 v[4:5], v[104:105], off
	v_lshl_add_u64 v[4:5], v[4:5], 0, s[12:13]
	s_waitcnt vmcnt(7)
	v_cvt_pk_bf16_f32 v108, v108, v109
	v_cvt_pk_bf16_f32 v109, v110, v111
	global_store_dwordx2 v[4:5], v[108:109], off
	v_lshl_add_u64 v[4:5], v[4:5], 0, s[12:13]
	s_waitcnt vmcnt(7)
	v_cvt_pk_bf16_f32 v112, v112, v113
	v_cvt_pk_bf16_f32 v113, v114, v115
	global_store_dwordx2 v[4:5], v[112:113], off
	v_lshl_add_u64 v[4:5], v[4:5], 0, s[12:13]
	s_waitcnt vmcnt(7)
	v_cvt_pk_bf16_f32 v116, v116, v117
	v_cvt_pk_bf16_f32 v117, v118, v119
	global_store_dwordx2 v[4:5], v[116:117], off
	v_lshl_add_u64 v[4:5], v[4:5], 0, s[12:13]
	s_waitcnt vmcnt(7)
	v_cvt_pk_bf16_f32 v120, v120, v121
	v_cvt_pk_bf16_f32 v121, v122, v123
	global_store_dwordx2 v[4:5], v[120:121], off
	v_lshl_add_u64 v[4:5], v[4:5], 0, s[12:13]
	s_waitcnt vmcnt(7)
	v_cvt_pk_bf16_f32 v124, v124, v125
	v_cvt_pk_bf16_f32 v125, v126, v127
	global_store_dwordx2 v[4:5], v[124:125], off
	v_lshl_add_u64 v[4:5], v[4:5], 0, s[12:13]
	s_waitcnt vmcnt(7)
	v_cvt_pk_bf16_f32 v128, v128, v129
	v_cvt_pk_bf16_f32 v129, v130, v131
	global_store_dwordx2 v[4:5], v[128:129], off
	v_lshl_add_u64 v[4:5], v[4:5], 0, s[12:13]
	s_sub_u32 s98, s98, 1
	s_cmp_lg_u32 s98, 0
	s_cbranch_scc1 .Lx8_loop
	v_cmp_ge_u64_e32 vcc, s[20:21], v[0:1]
	s_and_b64 exec, exec, vcc
	s_cbranch_execz .LBB0_141
.LBB0_140:
	v_lshl_add_u64 v[6:7], s[72:73], 0, v[2:3]
	v_lshl_add_u64 v[8:9], s[8:9], 0, v[2:3]
	v_cmp_gt_u64_e32 vcc, s[18:19], v[0:1]
	v_lshl_add_u64 v[0:1], v[0:1], 0, s[6:7]
	v_lshl_add_u64 v[2:3], v[2:3], 0, s[10:11]
	v_cndmask_b32_e32 v7, v9, v7, vcc
	v_cndmask_b32_e32 v6, v8, v6, vcc
	global_load_dwordx4 v[6:9], v[6:7], off nt
	v_cmp_lt_u64_e32 vcc, s[20:21], v[0:1]
	s_or_b64 s[16:17], vcc, s[16:17]
	s_waitcnt vmcnt(0)
	v_cvt_pk_bf16_f32 v6, v6, v7
	v_cvt_pk_bf16_f32 v7, v8, v9
	global_store_dwordx2 v[4:5], v[6:7], off
	v_lshl_add_u64 v[4:5], v[4:5], 0, s[12:13]
	s_andn2_b64 exec, exec, s[16:17]
	s_cbranch_execnz .LBB0_140

.LBB0_1033:
	v_ashrrev_i32_e32 v6, 3, v36
	v_ashrrev_i32_e32 v7, 31, v6
	v_lshlrev_b64 v[6:7], 10, v[6:7]
	v_readlane_b32 s16, v254, 15
	v_or_b32_e32 v6, v6, v18
	v_readlane_b32 s17, v254, 16
	s_add_i32 s10, s11, s3
	s_cmpk_lt_i32 s10, 0x2000
	v_lshl_add_u64 v[8:9], v[6:7], 2, s[16:17]
	global_load_dwordx4 v[40:43], v[8:9], off nt
	v_lshlrev_b64 v[38:39], 1, v[6:7]
	s_cselect_b32 s4, s10, s11
	v_lshl_add_u64 v[6:7], s[56:57], 0, v[38:39]
	global_load_dwordx2 v[44:45], v[6:7], off nt
	v_lshl_add_u32 v8, s4, 4, v1
	v_ashrrev_i32_e32 v8, 3, v8
	v_ashrrev_i32_e32 v9, 31, v8
	v_lshlrev_b64 v[24:25], 10, v[8:9]
	v_or_b32_e32 v24, v24, v18
	v_lshl_add_u64 v[8:9], v[24:25], 2, s[16:17]
	s_waitcnt lgkmcnt(0)
	global_load_dwordx4 v[10:13], v[8:9], off nt
	s_add_i32 s12, s9, s11
	s_cmpk_lt_i32 s12, 0x2000
	s_cselect_b64 s[4:5], -1, 0
	s_and_b64 s[6:7], s[4:5], exec
	s_mul_i32 s7, s3, 3
	s_cselect_b32 s6, s12, s11
	s_add_i32 s14, s7, s11
	s_cmpk_lt_i32 s14, 0x2000
	v_lshl_add_u32 v8, s6, 4, v1
	s_cselect_b64 s[6:7], -1, 0
	v_ashrrev_i32_e32 v8, 3, v8
	s_and_b64 s[12:13], s[6:7], exec
	v_ashrrev_i32_e32 v9, 31, v8
	s_cselect_b32 s11, s14, s11
	v_lshlrev_b64 v[26:27], 10, v[8:9]
	v_lshl_add_u32 v8, s11, 4, v1
	v_ashrrev_i32_e32 v8, 3, v8
	v_ashrrev_i32_e32 v9, 31, v8
	v_or_b32_e32 v26, v26, v18
	v_lshlrev_b64 v[20:21], 10, v[8:9]
	v_lshl_add_u64 v[6:7], v[24:25], 1, s[56:57]
	v_lshl_add_u64 v[14:15], v[26:27], 2, s[16:17]
	v_or_b32_e32 v20, v20, v18
	v_lshl_add_u64 v[28:29], v[26:27], 1, s[56:57]
	global_load_dwordx2 v[30:31], v[6:7], off nt
	s_nop 0
	global_load_dwordx4 v[14:17], v[14:15], off nt
	v_lshl_add_u64 v[6:7], v[20:21], 1, s[56:57]
	v_lshl_add_u64 v[8:9], v[20:21], 2, s[16:17]
	global_load_dwordx2 v[22:23], v[6:7], off nt
	s_nop 0
	global_load_dwordx2 v[28:29], v[28:29], off nt
	s_nop 0
	global_load_dwordx4 v[6:9], v[8:9], off nt
	s_cmpk_gt_i32 s10, 0x1fff
	s_waitcnt vmcnt(7)
	v_pk_mul_f32 v[46:47], v[42:43], v[42:43]
	v_pk_mul_f32 v[48:49], v[40:41], v[40:41]
	s_nop 0
	v_pk_mov_b32 v[50:51], v[48:49], v[46:47] op_sel:[1,0]
	v_mov_b32_e32 v49, v47
	v_pk_add_f32 v[46:47], v[50:51], v[48:49]
	s_waitcnt vmcnt(5)
	v_mul_f32_e32 v48, v13, v13
	v_add_f32_e32 v37, v46, v47
	ds_bpermute_b32 v46, v19, v37
	v_mul_f32_e32 v47, v11, v11
	v_fmac_f32_e32 v47, v10, v10
	v_fmac_f32_e32 v48, v12, v12
	v_add_f32_e32 v48, v47, v48
	s_waitcnt lgkmcnt(0)
	v_add_f32_e32 v37, v37, v46
	ds_bpermute_b32 v46, v32, v37
	ds_bpermute_b32 v49, v19, v48
	s_waitcnt lgkmcnt(1)
	v_add_f32_e32 v37, v37, v46
	ds_bpermute_b32 v50, v33, v37
	v_lshl_add_u64 v[46:47], s[36:37], 0, v[38:39]
	s_waitcnt lgkmcnt(1)
	v_add_f32_e32 v38, v48, v49
	ds_bpermute_b32 v39, v32, v38
	v_and_b32_e32 v49, 0xffff0000, v45
	s_waitcnt lgkmcnt(1)
	v_add_f32_e32 v37, v37, v50
	ds_bpermute_b32 v48, v34, v37
	s_waitcnt lgkmcnt(1)
	v_add_f32_e32 v38, v38, v39
	ds_bpermute_b32 v39, v33, v38
	s_waitcnt lgkmcnt(1)
	v_add_f32_e32 v37, v37, v48
	ds_bpermute_b32 v50, v35, v37
	v_lshlrev_b32_e32 v48, 16, v45
	s_waitcnt lgkmcnt(1)
	v_add_f32_e32 v38, v38, v39
	ds_bpermute_b32 v39, v34, v38
	v_and_b32_e32 v45, 0xffff0000, v44
	s_waitcnt lgkmcnt(1)
	v_add_f32_e32 v37, v37, v50
	v_fmamk_f32 v37, v37, 0x3c000000, v220
	v_mul_f32_e32 v50, 0x4b800000, v37
	v_cmp_gt_f32_e32 vcc, s83, v37
	v_lshlrev_b32_e32 v44, 16, v44
	s_nop 0
	v_cndmask_b32_e32 v37, v37, v50, vcc
	v_rsq_f32_e32 v50, v37
	s_waitcnt lgkmcnt(0)
	v_add_f32_e32 v37, v38, v39
	ds_bpermute_b32 v38, v35, v37
	v_mul_f32_e32 v39, 0x45800000, v50
	v_cndmask_b32_e32 v50, v50, v39, vcc
	v_pk_mul_f32 v[40:41], v[40:41], v[50:51] op_sel_hi:[1,0]
	v_pk_mul_f32 v[42:43], v[42:43], v[50:51] op_sel_hi:[1,0]
	v_pk_mul_f32 v[40:41], v[2:3], v[40:41]
	v_pk_mul_f32 v[42:43], v[4:5], v[42:43]
	v_pk_mul_f32 v[40:41], v[40:41], v[44:45]
	v_pk_mul_f32 v[42:43], v[42:43], v[48:49]
	v_cvt_pk_bf16_f32 v40, v40, v41
	s_nop 0
	v_cvt_pk_bf16_f32 v41, v42, v43
	global_store_dwordx2 v[46:47], v[40:41], off
	s_cbranch_scc1 .LBB0_1035
	s_waitcnt lgkmcnt(0)
	v_add_f32_e32 v37, v37, v38
	v_fmamk_f32 v37, v37, 0x3c000000, v220
	v_mul_f32_e32 v38, 0x4b800000, v37
	v_cmp_gt_f32_e32 vcc, s83, v37
	s_waitcnt vmcnt(5)
	v_and_b32_e32 v39, 0xffff0000, v31
	v_lshl_add_u64 v[24:25], v[24:25], 1, s[36:37]
	v_cndmask_b32_e32 v37, v37, v38, vcc
	v_rsq_f32_e32 v37, v37
	v_lshlrev_b32_e32 v38, 16, v31
	v_and_b32_e32 v31, 0xffff0000, v30
	v_lshlrev_b32_e32 v30, 16, v30
	v_mul_f32_e32 v40, 0x45800000, v37
	v_cndmask_b32_e32 v40, v37, v40, vcc
	v_pk_mul_f32 v[10:11], v[10:11], v[40:41] op_sel_hi:[1,0]
	v_pk_mul_f32 v[12:13], v[12:13], v[40:41] op_sel_hi:[1,0]
	v_pk_mul_f32 v[10:11], v[2:3], v[10:11]
	v_pk_mul_f32 v[12:13], v[4:5], v[12:13]
	v_pk_mul_f32 v[10:11], v[10:11], v[30:31]
	v_pk_mul_f32 v[12:13], v[12:13], v[38:39]
	v_cvt_pk_bf16_f32 v10, v10, v11
	s_nop 0
	v_cvt_pk_bf16_f32 v11, v12, v13
	global_store_dwordx2 v[24:25], v[10:11], off
